# v17 + NA output stores: 4x dwordx2 -> 2x dwordx4 via permlane16_swap (dt pairs), op count kept with one-lane dummies
# baseline (speedup 1.0000x reference)
; #define LAS __attribute__((address_space(3)))
; __device__ __forceinline__ f32x4 mfma16(bf16x8 a, bf16x8 b, f32x4 c) { return __builtin_amdgcn_mfma_f32_16x16x32_bf16(a, b, c, 0, 0, 0); }
; __device__ __forceinline__ void na_strip(const Params& P, LAS unsigned char* lds, int strip, int hsel, int tid, int lane, int wave) {
;     ...
;         const int start = na_start(myr, rows);
;         f32x4 sc[8][2];
; #pragma unroll
;         for (int j = 0; j < 8; ++j) { const LAS float* rpj = rp + (start + j - myr + 7) * 31;
; #pragma unroll
;             for (int kt = 0; kt < 2; ++kt)
; #pragma unroll
;                 for (int i = 0; i < 4; ++i) sc[j][kt][i] = rpj[bofs[kt][i]] + msk[kt][i]; }
; #pragma unroll
;         for (int j = 0; j < 8; ++j) { const LAS unsigned char* kt_ = lds + NA_KR + (unsigned)((start + j) % 9) * 8192u;
; #pragma unroll
;             for (int kt = 0; kt < 2; ++kt) { const unsigned key = kstart + 16 * kt + l15; const LAS unsigned char* kp = kt_ + key * 128;
;                 f32x4 a = sc[j][kt];
;                 a = mfma16(*(const LAS bf16x8*)(kp + 16 * ((unsigned)g ^ (key & 7))), qf[0], a);
;                 a = mfma16(*(const LAS bf16x8*)(kp + 16 * ((unsigned)(4 + g) ^ (key & 7))), qf[1], a);
;                 sc[j][kt] = a; } }
.LBB0_303:
	s_max_i32 s11, s21, 4
	s_add_i32 s11, s11, -4
	s_min_u32 s11, s11, s77
	s_add_i32 s11, s11, s20
	s_mulk_i32 s11, 0x7c
	s_add_i32 s11, s11, 0
	s_add_i32 s15, s11, 0x24000
	v_lshl_add_u32 v172, v63, 2, s15
	v_lshl_add_u32 v173, v65, 2, s15
	ds_read2_b32 v[44:45], v172 offset0:217 offset1:248
	ds_read2_b32 v[54:55], v173 offset0:217 offset1:248
	v_lshl_add_u32 v176, v96, 2, s15
	v_lshl_add_u32 v178, v98, 2, s15
	v_lshl_add_u32 v181, v100, 2, s15
	v_lshl_add_u32 v184, v155, 2, s15
	v_lshl_add_u32 v186, v157, 2, s15
	v_add_u32_e32 v226, 0x400, v172
	v_add_u32_e32 v227, 0x400, v173
	v_add_u32_e32 v228, 0x400, v176
	v_add_u32_e32 v229, 0x400, v178
	s_max_i32 s13, s48, 4
	ds_read2_b32 v[56:57], v176 offset0:217 offset1:248
	s_waitcnt lgkmcnt(2)
	v_add_f32_e32 v36, v62, v44
	s_waitcnt lgkmcnt(1)
	v_add_f32_e32 v37, v64, v54
	ds_read2_b32 v[58:59], v178 offset0:217 offset1:248
	ds_read2_b32 v[60:61], v181 offset0:217 offset1:248
	ds_read2_b32 v[166:167], v184 offset0:217 offset1:248
	ds_read2_b32 v[168:169], v186 offset0:217 offset1:248
	v_add_f32_e32 v54, v62, v45
	ds_read2_b32 v[44:45], v226 offset0:23 offset1:54
	ds_read2_b32 v[174:175], v227 offset0:23 offset1:54
	ds_read2_b32 v[176:177], v228 offset0:23 offset1:54
	ds_read2_b32 v[178:179], v229 offset0:23 offset1:54
	s_add_i32 s13, s13, -4
	s_min_u32 s11, s13, s77
	v_lshl_add_u32 v188, v159, 2, s15
	v_add_u32_e32 v238, 0x400, v186
	s_mul_i32 s13, s11, 57
	v_add_u32_e32 v181, 0x400, v181
	v_add_u32_e32 v236, 0x400, v184
	ds_read2_b32 v[186:187], v238 offset0:23 offset1:54
	v_add_u32_e32 v240, 0x400, v188
	s_bfe_u32 s13, s13, 0x70009
	s_waitcnt lgkmcnt(9)
	v_add_f32_e32 v38, v93, v56
	ds_read2_b32 v[170:171], v188 offset0:217 offset1:248
	s_waitcnt lgkmcnt(8)
	v_add_f32_e32 v40, v99, v60
	s_waitcnt lgkmcnt(7)
	v_add_f32_e32 v41, v101, v166
	s_waitcnt lgkmcnt(6)
	v_add_f32_e32 v42, v156, v168
	v_add_f32_e32 v56, v93, v57
	v_add_f32_e32 v57, v97, v59
	v_add_f32_e32 v59, v101, v167
	v_add_f32_e32 v60, v156, v169
	s_waitcnt lgkmcnt(5)
	v_add_f32_e32 v166, v62, v44
	s_waitcnt lgkmcnt(4)
	v_add_f32_e32 v167, v64, v174
	s_waitcnt lgkmcnt(3)
	v_add_f32_e32 v168, v93, v176
	ds_read2_b32 v[182:183], v181 offset0:23 offset1:54
	ds_read2_b32 v[184:185], v236 offset0:23 offset1:54
	ds_read2_b32 v[188:189], v240 offset0:23 offset1:54
	s_waitcnt lgkmcnt(5)
	v_add_f32_e32 v169, v97, v178
	v_add_f32_e32 v174, v62, v45
	v_add_f32_e32 v176, v93, v177
	v_add_f32_e32 v177, v97, v179
	ds_read2_b32 v[44:45], v226 offset0:85 offset1:116
	ds_read2_b32 v[178:179], v227 offset0:85 offset1:116
	s_mul_i32 s13, s13, 9
	s_sub_i32 s13, s11, s13
	s_and_b32 s13, s13, 0xff
	s_lshl_b32 s25, s13, 13
	s_add_i32 s13, s11, 1
	s_waitcnt lgkmcnt(6)
	v_add_f32_e32 v172, v156, v186
	s_waitcnt lgkmcnt(1)
	v_add_f32_e32 v186, v62, v44
	v_add_u32_e32 v44, s25, v165
	s_and_b32 s15, s13, 0xff
	v_add_f32_e32 v39, v97, v58
	v_add_f32_e32 v58, v99, v61
	v_add_f32_e32 v61, v158, v171
	v_add_f32_e32 v171, v101, v184
	v_add_f32_e32 v184, v156, v187
	s_waitcnt lgkmcnt(0)
	v_add_f32_e32 v187, v64, v178
	v_add_u32_e32 v178, v44, v69
	s_mul_i32 s15, s15, 57
	ds_read_b128 v[190:193], v178
	ds_read2_b32 v[214:215], v228 offset0:85 offset1:116
	ds_read2_b32 v[216:217], v229 offset0:85 offset1:116
	s_bfe_u32 s15, s15, 0x70009
	v_add_u32_e32 v44, v44, v107
	s_mul_i32 s15, s15, 9
	ds_read_b128 v[194:197], v44
	ds_read2_b32 v[218:219], v181 offset0:85 offset1:116
	ds_read_b128 v[198:201], v178 offset:2048
	s_sub_i32 s13, s13, s15
	s_waitcnt lgkmcnt(5)
	v_mfma_f32_16x16x32_bf16 v[36:39], v[190:193], v[30:33], v[36:39]
	s_and_b32 s13, s13, 0xff
	s_lshl_b32 s48, s13, 13
	ds_read2_b32 v[220:221], v236 offset0:85 offset1:116
	ds_read_b128 v[202:205], v44 offset:2048
	v_add_u32_e32 v44, s48, v165
	v_add_u32_e32 v178, v44, v69
	s_waitcnt lgkmcnt(4)
	v_mfma_f32_16x16x32_bf16 v[194:197], v[194:197], v[26:29], v[36:39]
	v_add_f32_e32 v43, v158, v170
	v_add_u32_e32 v44, v44, v107
	s_add_i32 s13, s11, 2
	ds_read_b128 v[36:39], v178
	s_waitcnt lgkmcnt(3)
	v_mfma_f32_16x16x32_bf16 v[40:43], v[198:201], v[30:33], v[40:43]
	ds_read_b128 v[198:201], v44
	s_and_b32 s15, s13, 0xff
	s_mul_i32 s15, s15, 57
	s_bfe_u32 s15, s15, 0x70009
	s_mul_i32 s15, s15, 9
	v_add_f32_e32 v55, v64, v55
	s_waitcnt lgkmcnt(2)
	v_mfma_f32_16x16x32_bf16 v[202:205], v[202:205], v[26:29], v[40:43]
	s_sub_i32 s13, s13, s15
	s_and_b32 s13, s13, 0xff
	s_lshl_b32 s35, s13, 13
	ds_read_b128 v[40:43], v178 offset:2048
	s_waitcnt lgkmcnt(2)
	v_mfma_f32_16x16x32_bf16 v[36:39], v[36:39], v[30:33], v[54:57]
	s_add_i32 s13, s11, 3
	s_and_b32 s15, s13, 0xff
	s_mul_i32 s15, s15, 57
	ds_read_b128 v[54:57], v44 offset:2048
	v_add_u32_e32 v44, s35, v165
	v_add_u32_e32 v178, v44, v69
	s_waitcnt lgkmcnt(2)
	v_mfma_f32_16x16x32_bf16 v[198:201], v[198:201], v[26:29], v[36:39]
	v_add_u32_e32 v44, v44, v107
	ds_read_b128 v[206:209], v44
	s_bfe_u32 s15, s15, 0x70009
	ds_read_b128 v[36:39], v178
	s_waitcnt lgkmcnt(3)
	v_mfma_f32_16x16x32_bf16 v[40:43], v[40:43], v[30:33], v[58:61]
	s_mul_i32 s15, s15, 9
	s_sub_i32 s13, s13, s15
	s_and_b32 s13, s13, 0xff
	s_waitcnt lgkmcnt(2)
	v_mfma_f32_16x16x32_bf16 v[210:213], v[54:57], v[26:29], v[40:43]
	s_lshl_b32 s17, s13, 13
	v_add_f32_e32 v58, v62, v45
	v_add_f32_e32 v170, v99, v182
	ds_read_b128 v[40:43], v178 offset:2048
	s_waitcnt lgkmcnt(1)
	v_mfma_f32_16x16x32_bf16 v[36:39], v[36:39], v[30:33], v[166:169]
	v_add_f32_e32 v173, v158, v188
	v_add_f32_e32 v188, v93, v214
	s_add_i32 s13, s11, 4
	ds_read_b128 v[166:169], v44 offset:2048
	v_add_u32_e32 v44, s17, v165
	v_add_u32_e32 v45, v44, v69
	v_mfma_f32_16x16x32_bf16 v[206:209], v[206:209], v[26:29], v[36:39]
	v_add_u32_e32 v214, v44, v107
	s_and_b32 s15, s13, 0xff
	s_mul_i32 s15, s15, 57
	ds_read_b128 v[36:39], v45
	s_waitcnt lgkmcnt(2)
; #define LAS __attribute__((address_space(3)))
; __device__ __forceinline__ f32x4 mfma16(bf16x8 a, bf16x8 b, f32x4 c) { return __builtin_amdgcn_mfma_f32_16x16x32_bf16(a, b, c, 0, 0, 0); }
; __device__ __forceinline__ void na_strip(const Params& P, LAS unsigned char* lds, int strip, int hsel, int tid, int lane, int wave) {
;     ...
;         u32x2 gv[4];
; #pragma unroll
;         for (int dt = 0; dt < 4; ++dt) gv[dt] = *(const u32x2*)(GA + tq * 512 + h * 64 + 16 * dt + 4 * g);
;         const int start = na_start(myr, rows);
;         f32x4 sc[8][2];
; #pragma unroll
;         for (int j = 0; j < 8; ++j) { const LAS float* rpj = rp + (start + j - myr + 7) * 31;
; #pragma unroll
;             for (int kt = 0; kt < 2; ++kt)
; #pragma unroll
;                 for (int i = 0; i < 4; ++i) sc[j][kt][i] = rpj[bofs[kt][i]] + msk[kt][i]; }
; #pragma unroll
;         for (int j = 0; j < 8; ++j) { const LAS unsigned char* kt_ = lds + NA_KR + (unsigned)((start + j) % 9) * 8192u;
; #pragma unroll
;             for (int kt = 0; kt < 2; ++kt) { const unsigned key = kstart + 16 * kt + l15; const LAS unsigned char* kp = kt_ + key * 128;
;                 f32x4 a = sc[j][kt];
;                 a = mfma16(*(const LAS bf16x8*)(kp + 16 * ((unsigned)g ^ (key & 7))), qf[0], a);
;                 a = mfma16(*(const LAS bf16x8*)(kp + 16 * ((unsigned)(4 + g) ^ (key & 7))), qf[1], a);
;                 sc[j][kt] = a; } }
; #pragma unroll
;         for (int j = 0; j < 8; ++j)
; #pragma unroll
;             for (int kt = 0; kt < 2; ++kt)
; #pragma unroll
;                 for (int i = 0; i < 4; ++i) sc[j][kt][i] = __builtin_amdgcn_exp2f(sc[j][kt][i]);
	v_mfma_f32_16x16x32_bf16 v[40:43], v[40:43], v[30:33], v[170:173]
	s_bfe_u32 s15, s15, 0x70009
	s_mul_i32 s15, s15, 9
	v_add_f32_e32 v175, v64, v175
	ds_read_b128 v[170:173], v214
	s_waitcnt lgkmcnt(2)
	v_mfma_f32_16x16x32_bf16 v[166:169], v[166:169], v[26:29], v[40:43]
	s_sub_i32 s13, s13, s15
	s_and_b32 s13, s13, 0xff
	s_lshl_b32 s16, s13, 13
	ds_read_b128 v[40:43], v45 offset:2048
	s_waitcnt lgkmcnt(2)
	v_mfma_f32_16x16x32_bf16 v[36:39], v[36:39], v[30:33], v[174:177]
	ds_read2_b32 v[222:223], v238 offset0:85 offset1:116
	ds_read2_b32 v[224:225], v240 offset0:85 offset1:116
	v_add_f32_e32 v59, v64, v179
	ds_read2_b32 v[44:45], v226 offset0:147 offset1:178
	ds_read2_b32 v[178:179], v227 offset0:147 offset1:178
	ds_read_b128 v[174:177], v214 offset:2048
	v_add_u32_e32 v214, s16, v165
	v_add_f32_e32 v60, v93, v215
	v_add_u32_e32 v215, v214, v69
	s_waitcnt lgkmcnt(6)
	v_mfma_f32_16x16x32_bf16 v[170:173], v[170:173], v[26:29], v[36:39]
	v_add_f32_e32 v182, v99, v183
	v_add_f32_e32 v183, v101, v185
	v_add_f32_e32 v185, v158, v189
	ds_read_b128 v[36:39], v215
	v_add_f32_e32 v190, v99, v218
	v_add_u32_e32 v218, v214, v107
	s_add_i32 s13, s11, 5
	s_waitcnt lgkmcnt(6)
	v_mfma_f32_16x16x32_bf16 v[40:43], v[40:43], v[30:33], v[182:185]
	s_and_b32 s15, s13, 0xff
	s_mul_i32 s15, s15, 57
	s_bfe_u32 s15, s15, 0x70009
	ds_read_b128 v[182:185], v218
	s_mul_i32 s15, s15, 9
	v_add_f32_e32 v189, v97, v216
	v_add_f32_e32 v61, v97, v217
	ds_read_b128 v[214:217], v215 offset:2048
	s_sub_i32 s13, s13, s15
	s_waitcnt lgkmcnt(2)
	v_mfma_f32_16x16x32_bf16 v[36:39], v[36:39], v[30:33], v[186:189]
	s_and_b32 s13, s13, 0xff
	s_lshl_b32 s15, s13, 13
	ds_read2_b32 v[230:231], v228 offset0:147 offset1:178
	v_mfma_f32_16x16x32_bf16 v[174:177], v[174:177], v[26:29], v[40:43]
	ds_read2_b32 v[232:233], v229 offset0:147 offset1:178
	ds_read_b128 v[186:189], v218 offset:2048
	v_add_f32_e32 v191, v101, v220
	v_add_u32_e32 v43, s15, v165
	v_add_f32_e32 v40, v62, v44
	v_add_u32_e32 v44, v43, v69
	s_waitcnt lgkmcnt(4)
	v_mfma_f32_16x16x32_bf16 v[182:185], v[182:185], v[26:29], v[36:39]
	v_add_f32_e32 v192, v156, v222
	v_add_f32_e32 v193, v158, v224
	v_add_f32_e32 v41, v64, v178
	ds_read_b128 v[36:39], v44
	v_add_u32_e32 v178, v43, v107
	s_add_i32 s13, s11, 6
	s_waitcnt lgkmcnt(4)
	v_mfma_f32_16x16x32_bf16 v[190:193], v[214:217], v[30:33], v[190:193]
	ds_read_b128 v[214:217], v178
	s_and_b32 s26, s13, 0xff
	v_add_f32_e32 v54, v99, v219
	v_add_f32_e32 v55, v101, v221
	ds_read_b128 v[218:221], v44 offset:2048
	s_mul_i32 s26, s26, 57
	s_bfe_u32 s26, s26, 0x70009
	s_mul_i32 s26, s26, 9
	s_sub_i32 s13, s13, s26
	s_waitcnt lgkmcnt(2)
	v_mfma_f32_16x16x32_bf16 v[36:39], v[36:39], v[30:33], v[58:61]
	s_and_b32 s13, s13, 0xff
	s_lshl_b32 s13, s13, 13
	v_add_u32_e32 v44, s13, v165
	ds_read2_b32 v[234:235], v181 offset0:147 offset1:178
	ds_read2_b32 v[236:237], v236 offset0:147 offset1:178
	ds_read2_b32 v[238:239], v238 offset0:147 offset1:178
	ds_read_b128 v[58:61], v178 offset:2048
	v_add_u32_e32 v178, v44, v69
	v_add_f32_e32 v56, v156, v223
	v_add_f32_e32 v57, v158, v225
	s_waitcnt lgkmcnt(5)
	v_mfma_f32_16x16x32_bf16 v[214:217], v[214:217], v[26:29], v[36:39]
	v_add_u32_e32 v44, v44, v107
	s_add_i32 s11, s11, 7
	s_and_b32 s26, s11, 0xff
	ds_read_b128 v[36:39], v178
	s_waitcnt lgkmcnt(5)
	v_mfma_f32_16x16x32_bf16 v[54:57], v[218:221], v[30:33], v[54:57]
	ds_read_b128 v[218:221], v44
	ds_read_b128 v[226:229], v44 offset:2048
	s_mul_i32 s26, s26, 57
	s_waitcnt lgkmcnt(3)
	v_mfma_f32_16x16x32_bf16 v[222:225], v[58:61], v[26:29], v[54:57]
	s_bfe_u32 s26, s26, 0x70009
	s_mul_i32 s26, s26, 9
	v_add_f32_e32 v42, v93, v230
	ds_read_b128 v[54:57], v178 offset:2048
	v_add_f32_e32 v43, v97, v232
	ds_read2_b32 v[240:241], v240 offset0:147 offset1:178
	s_sub_i32 s11, s11, s26
	s_waitcnt lgkmcnt(4)
	v_mfma_f32_16x16x32_bf16 v[36:39], v[36:39], v[30:33], v[40:43]
	s_and_b32 s11, s11, 0xff
	s_lshl_b32 s11, s11, 13
	v_add_f32_e32 v58, v62, v45
	v_add_u32_e32 v40, s11, v165
	v_add_u32_e32 v178, v40, v69
	v_mfma_f32_16x16x32_bf16 v[186:189], v[186:189], v[26:29], v[190:193]
	v_add_u32_e32 v181, v40, v107
	v_add_f32_e32 v59, v64, v179
	v_add_f32_e32 v60, v93, v231
	v_add_f32_e32 v190, v99, v234
	v_add_f32_e32 v191, v101, v236
	v_add_f32_e32 v192, v156, v238
	s_waitcnt lgkmcnt(0)
	v_add_f32_e32 v193, v158, v240
	v_mfma_f32_16x16x32_bf16 v[42:45], v[218:221], v[26:29], v[36:39]
	ds_read_b128 v[218:221], v178
	v_add_f32_e32 v61, v97, v233
	v_exp_f32_e32 v230, v182
	v_mfma_f32_16x16x32_bf16 v[36:39], v[54:57], v[30:33], v[190:193]
	ds_read_b128 v[54:57], v181
	v_exp_f32_e32 v231, v183
	v_exp_f32_e32 v232, v184
	ds_read_b128 v[190:193], v178 offset:2048
	v_mfma_f32_16x16x32_bf16 v[38:41], v[226:229], v[26:29], v[36:39]
	ds_read_b128 v[226:229], v181 offset:2048
	v_lshl_add_u64 v[178:179], v[48:49], 0, v[34:35]
	v_exp_f32_e32 v181, v204
	s_waitcnt lgkmcnt(3)
	v_mfma_f32_16x16x32_bf16 v[58:61], v[218:221], v[30:33], v[58:61]
	v_add_f32_e32 v218, v99, v235
	v_add_f32_e32 v219, v101, v237
	v_add_f32_e32 v220, v156, v239
	v_add_f32_e32 v221, v158, v241
	s_waitcnt lgkmcnt(2)
	v_mfma_f32_16x16x32_bf16 v[34:37], v[54:57], v[26:29], v[58:61]
	s_nop 2
	global_load_dwordx2 v[60:61], v[178:179], off
	global_load_dwordx2 v[58:59], v[178:179], off offset:32
	global_load_dwordx2 v[56:57], v[178:179], off offset:64
	global_load_dwordx2 v[54:55], v[178:179], off offset:96
	v_exp_f32_e32 v178, v202
	v_exp_f32_e32 v179, v203
	s_waitcnt lgkmcnt(1)
	v_mfma_f32_16x16x32_bf16 v[30:33], v[190:193], v[30:33], v[218:221]
	v_exp_f32_e32 v190, v205
	v_exp_f32_e32 v191, v198
	v_exp_f32_e32 v198, v213
	s_waitcnt lgkmcnt(0)
; __device__ __forceinline__ unsigned cvt_pk_bf16(float lo, float hi) { unsigned r; asm volatile("v_cvt_pk_bf16_f32 %0, %1, %2" : "=v"(r) : "v"(lo), "v"(hi)); return r; }
; #define LAS __attribute__((address_space(3)))
; __device__ __forceinline__ s16x4 tr_read(const LAS unsigned char* p) { return __builtin_amdgcn_ds_read_tr16_b64_v4i16((LAS s16x4*)p); }
; __device__ __forceinline__ bf16x8 cat8(s16x4 a, s16x4 b) { return (bf16x8){a[0], a[1], a[2], a[3], b[0], b[1], b[2], b[3]}; }
; __device__ __forceinline__ f32x4 mfma16(bf16x8 a, bf16x8 b, f32x4 c) { return __builtin_amdgcn_mfma_f32_16x16x32_bf16(a, b, c, 0, 0, 0); }
; __device__ __forceinline__ void na_strip(const Params& P, LAS unsigned char* lds, int strip, int hsel, int tid, int lane, int wave) {
;     ...
;                 for (int i = 0; i < 4; ++i) sc[j][kt][i] = __builtin_amdgcn_exp2f(sc[j][kt][i]);
;         f32x4 o[4], osum = (f32x4){0.f, 0.f, 0.f, 0.f};
; #pragma unroll
;         for (int dt = 0; dt < 4; ++dt) o[dt] = (f32x4){0.f, 0.f, 0.f, 0.f};
;         const bf16x8 ones8 = (bf16x8){0x3f80, 0x3f80, 0x3f80, 0x3f80, 0x3f80, 0x3f80, 0x3f80, 0x3f80};
; #pragma unroll
;         for (int j = 0; j < 8; ++j) {
;             u32x4 pw; pw.x = cvt_pk_bf16(sc[j][0][0], sc[j][0][1]); pw.y = cvt_pk_bf16(sc[j][0][2], sc[j][0][3]); pw.z = cvt_pk_bf16(sc[j][1][0], sc[j][1][1]); pw.w = cvt_pk_bf16(sc[j][1][2], sc[j][1][3]);
;             const bf16x8 pb = __builtin_bit_cast(bf16x8, pw);
;             const LAS unsigned char* vt = lds + NA_VR + (unsigned)((start + j) % 9) * 8192u;
;             const unsigned k0 = kstart + 4 * g + q4, k1 = k0 + 16;
;             const unsigned x0 = 4 * ((k0 >> 1) & 3), x1 = 4 * ((k1 >> 1) & 3);
; #pragma unroll
;             for (int dt = 0; dt < 4; ++dt) {
;                 const bf16x8 va = cat8(tr_read(vt + k0 * 128 + 8 * ((unsigned)(4 * dt + p) ^ x0)), tr_read(vt + k1 * 128 + 8 * ((unsigned)(4 * dt + p) ^ x1)));
;                 o[dt] = mfma16(va, pb, o[dt]); }
;             osum = mfma16(ones8, pb, osum);
;         }
	v_mfma_f32_16x16x32_bf16 v[26:29], v[226:229], v[26:29], v[30:33]
	v_exp_f32_e32 v213, v169
	v_exp_f32_e32 v192, v199
	v_exp_f32_e32 v220, v172
	v_exp_f32_e32 v30, v194
	v_exp_f32_e32 v31, v195
	v_exp_f32_e32 v32, v196
	v_exp_f32_e32 v33, v197
	v_exp_f32_e32 v195, v210
	v_exp_f32_e32 v196, v211
	v_exp_f32_e32 v197, v212
	v_exp_f32_e32 v210, v166
	v_exp_f32_e32 v211, v167
	v_exp_f32_e32 v212, v168
	v_cvt_pk_bf16_f32 v166, v30, v31
	v_cvt_pk_bf16_f32 v167, v32, v33
	v_cvt_pk_bf16_f32 v168, v178, v179
	v_add_u32_e32 v178, s25, v160
	v_add_u32_e32 v32, v178, v161
	v_cvt_pk_bf16_f32 v169, v181, v190
	ds_read_b64_tr_b16 v[30:31], v32
	ds_read_b64_tr_b16 v[32:33], v32 offset:2048
	v_exp_f32_e32 v228, v176
	v_exp_f32_e32 v233, v185
	v_add_u32_e32 v172, v178, v162
	v_add_u32_e32 v176, v178, v163
	s_waitcnt lgkmcnt(0)
	v_mfma_f32_16x16x32_bf16 v[182:185], v[30:33], v[166:169], 0
	v_add_u32_e32 v30, v178, v164
	v_add_u32_e32 v178, s48, v160
	v_exp_f32_e32 v193, v200
	v_exp_f32_e32 v194, v201
	v_exp_f32_e32 v218, v170
	v_exp_f32_e32 v219, v171
	v_exp_f32_e32 v221, v173
	v_exp_f32_e32 v226, v174
	v_exp_f32_e32 v227, v175
	v_exp_f32_e32 v229, v177
	v_exp_f32_e32 v234, v186
	v_exp_f32_e32 v235, v187
	v_exp_f32_e32 v179, v188
	ds_read_b64_tr_b16 v[170:171], v172
	ds_read_b64_tr_b16 v[172:173], v172 offset:2048
	v_exp_f32_e32 v181, v189
	ds_read_b64_tr_b16 v[174:175], v176
	ds_read_b64_tr_b16 v[176:177], v176 offset:2048
	ds_read_b64_tr_b16 v[186:187], v30
	ds_read_b64_tr_b16 v[188:189], v30 offset:2048
	v_cvt_pk_bf16_f32 v190, v191, v192
	v_cvt_pk_bf16_f32 v191, v193, v194
	v_cvt_pk_bf16_f32 v192, v195, v196
	v_add_u32_e32 v196, v178, v161
	v_cvt_pk_bf16_f32 v193, v197, v198
	ds_read_b64_tr_b16 v[194:195], v196
	ds_read_b64_tr_b16 v[196:197], v196 offset:2048
	s_mov_b32 s26, s24
	s_mov_b32 s27, s24
	s_mov_b32 s25, s24
	v_mov_b64_e32 v[32:33], s[26:27]
	v_add_u32_e32 v200, v178, v162
	v_add_u32_e32 v204, v178, v163
	v_add_u32_e32 v178, v178, v164
	v_mov_b64_e32 v[30:31], s[24:25]
	ds_read_b64_tr_b16 v[198:199], v200
	ds_read_b64_tr_b16 v[200:201], v200 offset:2048
	ds_read_b64_tr_b16 v[202:203], v204
	ds_read_b64_tr_b16 v[204:205], v204 offset:2048
	s_waitcnt lgkmcnt(4)
	v_mfma_f32_16x16x32_bf16 v[182:185], v[194:197], v[190:193], v[182:185]
	ds_read_b64_tr_b16 v[194:195], v178
	ds_read_b64_tr_b16 v[196:197], v178 offset:2048
	v_add_u32_e32 v178, s35, v160
	v_exp_f32_e32 v206, v206
	v_mfma_f32_16x16x32_bf16 v[174:177], v[174:177], v[166:169], 0
	v_exp_f32_e32 v207, v207
	v_exp_f32_e32 v208, v208
	v_exp_f32_e32 v209, v209
	v_mfma_f32_16x16x32_bf16 v[186:189], v[186:189], v[166:169], 0
	v_exp_f32_e32 v214, v214
	v_exp_f32_e32 v215, v215
	v_exp_f32_e32 v216, v216
	v_mfma_f32_16x16x32_bf16 v[170:173], v[170:173], v[166:169], 0
	v_exp_f32_e32 v217, v217
	v_exp_f32_e32 v222, v222
	v_exp_f32_e32 v223, v223
	v_mfma_f32_16x16x32_bf16 v[166:169], v[30:33], v[166:169], 0
	s_and_b64 vcc, exec, s[4:5]
	s_waitcnt lgkmcnt(2)
	v_mfma_f32_16x16x32_bf16 v[174:177], v[202:205], v[190:193], v[174:177]
	v_add_u32_e32 v204, v178, v161
	s_waitcnt lgkmcnt(0)
	v_mfma_f32_16x16x32_bf16 v[186:189], v[194:197], v[190:193], v[186:189]
	v_add_u32_e32 v196, v178, v162
	v_mfma_f32_16x16x32_bf16 v[170:173], v[198:201], v[190:193], v[170:173]
	v_cvt_pk_bf16_f32 v198, v206, v207
	v_cvt_pk_bf16_f32 v199, v208, v209
	v_cvt_pk_bf16_f32 v200, v210, v211
	v_cvt_pk_bf16_f32 v201, v212, v213
	ds_read_b64_tr_b16 v[202:203], v204
	ds_read_b64_tr_b16 v[204:205], v204 offset:2048
	ds_read_b64_tr_b16 v[194:195], v196
	ds_read_b64_tr_b16 v[196:197], v196 offset:2048
	v_mfma_f32_16x16x32_bf16 v[166:169], v[30:33], v[190:193], v[166:169]
	v_add_u32_e32 v192, v178, v163
	ds_read_b64_tr_b16 v[190:191], v192
	ds_read_b64_tr_b16 v[192:193], v192 offset:2048
	v_exp_f32_e32 v208, v42
	v_add_u32_e32 v42, v178, v164
	s_waitcnt lgkmcnt(2)
	v_mfma_f32_16x16x32_bf16 v[170:173], v[194:197], v[198:201], v[170:173]
	ds_read_b64_tr_b16 v[194:195], v42
	ds_read_b64_tr_b16 v[196:197], v42 offset:2048
	v_add_u32_e32 v178, s17, v160
	v_add_u32_e32 v42, v178, v161
	v_mfma_f32_16x16x32_bf16 v[182:185], v[202:205], v[198:201], v[182:185]
	v_exp_f32_e32 v206, v224
	v_exp_f32_e32 v207, v225
	s_waitcnt lgkmcnt(2)
	v_mfma_f32_16x16x32_bf16 v[174:177], v[190:193], v[198:201], v[174:177]
	v_cvt_pk_bf16_f32 v190, v218, v219
	v_cvt_pk_bf16_f32 v191, v220, v221
	v_cvt_pk_bf16_f32 v192, v226, v227
	v_cvt_pk_bf16_f32 v193, v228, v229
	ds_read_b64_tr_b16 v[202:203], v42
	ds_read_b64_tr_b16 v[204:205], v42 offset:2048
	v_add_u32_e32 v42, v178, v162
	s_waitcnt lgkmcnt(2)
	v_mfma_f32_16x16x32_bf16 v[186:189], v[194:197], v[198:201], v[186:189]
	ds_read_b64_tr_b16 v[194:195], v42
	ds_read_b64_tr_b16 v[196:197], v42 offset:2048
	v_add_u32_e32 v42, v178, v163
	v_mfma_f32_16x16x32_bf16 v[166:169], v[30:33], v[198:201], v[166:169]
	ds_read_b64_tr_b16 v[198:199], v42
	ds_read_b64_tr_b16 v[200:201], v42 offset:2048
	s_waitcnt lgkmcnt(4)
	v_mfma_f32_16x16x32_bf16 v[182:185], v[202:205], v[190:193], v[182:185]
	v_exp_f32_e32 v202, v43
	v_exp_f32_e32 v203, v44
	v_exp_f32_e32 v204, v45
	s_waitcnt lgkmcnt(2)
	v_mfma_f32_16x16x32_bf16 v[42:45], v[194:197], v[190:193], v[170:173]
	v_exp_f32_e32 v205, v40
	s_nop 1
	v_add_u32_e32 v172, v178, v164
	ds_read_b64_tr_b16 v[170:171], v172
	ds_read_b64_tr_b16 v[172:173], v172 offset:2048
	v_add_u32_e32 v178, s16, v160
	v_cvt_pk_bf16_f32 v194, v230, v231
	v_cvt_pk_bf16_f32 v195, v232, v233
	v_cvt_pk_bf16_f32 v196, v234, v235
	v_cvt_pk_bf16_f32 v197, v179, v181
	v_add_u32_e32 v179, v178, v161
	s_waitcnt lgkmcnt(2)
; __device__ __forceinline__ unsigned cvt_pk_bf16(float lo, float hi) { unsigned r; asm volatile("v_cvt_pk_bf16_f32 %0, %1, %2" : "=v"(r) : "v"(lo), "v"(hi)); return r; }
; #define LAS __attribute__((address_space(3)))
; __device__ __forceinline__ s16x4 tr_read(const LAS unsigned char* p) { return __builtin_amdgcn_ds_read_tr16_b64_v4i16((LAS s16x4*)p); }
; __device__ __forceinline__ bf16x8 cat8(s16x4 a, s16x4 b) { return (bf16x8){a[0], a[1], a[2], a[3], b[0], b[1], b[2], b[3]}; }
; __device__ __forceinline__ f32x4 mfma16(bf16x8 a, bf16x8 b, f32x4 c) { return __builtin_amdgcn_mfma_f32_16x16x32_bf16(a, b, c, 0, 0, 0); }
; __device__ __forceinline__ void na_strip(const Params& P, LAS unsigned char* lds, int strip, int hsel, int tid, int lane, int wave) {
;     ...
; #pragma unroll
;         for (int j = 0; j < 8; ++j) {
;             u32x4 pw; pw.x = cvt_pk_bf16(sc[j][0][0], sc[j][0][1]); pw.y = cvt_pk_bf16(sc[j][0][2], sc[j][0][3]); pw.z = cvt_pk_bf16(sc[j][1][0], sc[j][1][1]); pw.w = cvt_pk_bf16(sc[j][1][2], sc[j][1][3]);
;             const bf16x8 pb = __builtin_bit_cast(bf16x8, pw);
;             const LAS unsigned char* vt = lds + NA_VR + (unsigned)((start + j) % 9) * 8192u;
;             const unsigned k0 = kstart + 4 * g + q4, k1 = k0 + 16;
;             const unsigned x0 = 4 * ((k0 >> 1) & 3), x1 = 4 * ((k1 >> 1) & 3);
; #pragma unroll
;             for (int dt = 0; dt < 4; ++dt) {
;                 const bf16x8 va = cat8(tr_read(vt + k0 * 128 + 8 * ((unsigned)(4 * dt + p) ^ x0)), tr_read(vt + k1 * 128 + 8 * ((unsigned)(4 * dt + p) ^ x1)));
;                 o[dt] = mfma16(va, pb, o[dt]); }
;             osum = mfma16(ones8, pb, osum);
;         }
	v_mfma_f32_16x16x32_bf16 v[174:177], v[198:201], v[190:193], v[174:177]
	ds_read_b64_tr_b16 v[198:199], v179
	ds_read_b64_tr_b16 v[200:201], v179 offset:2048
	v_add_u32_e32 v179, v178, v162
	v_exp_f32_e32 v181, v39
	s_waitcnt lgkmcnt(2)
	v_mfma_f32_16x16x32_bf16 v[170:173], v[170:173], v[190:193], v[186:189]
	s_nop 2
	ds_read_b64_tr_b16 v[186:187], v179
	ds_read_b64_tr_b16 v[188:189], v179 offset:2048
	v_add_u32_e32 v179, v178, v163
	v_mfma_f32_16x16x32_bf16 v[166:169], v[30:33], v[190:193], v[166:169]
	ds_read_b64_tr_b16 v[190:191], v179
	ds_read_b64_tr_b16 v[192:193], v179 offset:2048
	v_exp_f32_e32 v179, v38
	v_add_u32_e32 v38, v178, v164
	s_waitcnt lgkmcnt(2)
	v_mfma_f32_16x16x32_bf16 v[42:45], v[186:189], v[194:197], v[42:45]
	ds_read_b64_tr_b16 v[186:187], v38
	ds_read_b64_tr_b16 v[188:189], v38 offset:2048
	v_add_u32_e32 v178, s15, v160
	v_add_u32_e32 v38, v178, v161
	v_mfma_f32_16x16x32_bf16 v[182:185], v[198:201], v[194:197], v[182:185]
	s_waitcnt lgkmcnt(2)
	v_mfma_f32_16x16x32_bf16 v[174:177], v[190:193], v[194:197], v[174:177]
	v_cvt_pk_bf16_f32 v190, v214, v215
	v_cvt_pk_bf16_f32 v191, v216, v217
	v_cvt_pk_bf16_f32 v192, v222, v223
	v_cvt_pk_bf16_f32 v193, v206, v207
	ds_read_b64_tr_b16 v[198:199], v38
	ds_read_b64_tr_b16 v[200:201], v38 offset:2048
	v_add_u32_e32 v38, v178, v162
	s_waitcnt lgkmcnt(2)
	v_mfma_f32_16x16x32_bf16 v[170:173], v[186:189], v[194:197], v[170:173]
	ds_read_b64_tr_b16 v[186:187], v38
	ds_read_b64_tr_b16 v[188:189], v38 offset:2048
	v_add_u32_e32 v38, v178, v163
	v_mfma_f32_16x16x32_bf16 v[166:169], v[30:33], v[194:197], v[166:169]
	ds_read_b64_tr_b16 v[194:195], v38
	ds_read_b64_tr_b16 v[196:197], v38 offset:2048
	s_waitcnt lgkmcnt(4)
	v_mfma_f32_16x16x32_bf16 v[182:185], v[198:201], v[190:193], v[182:185]
	v_exp_f32_e32 v199, v34
	v_add_u32_e32 v34, v178, v164
	v_exp_f32_e32 v198, v41
	s_waitcnt lgkmcnt(2)
	v_mfma_f32_16x16x32_bf16 v[38:41], v[186:189], v[190:193], v[42:45]
	s_nop 2
	ds_read_b64_tr_b16 v[42:43], v34
	ds_read_b64_tr_b16 v[44:45], v34 offset:2048
	v_add_u32_e32 v34, s13, v160
	v_exp_f32_e32 v200, v35
	v_add_u32_e32 v35, v34, v161
	s_waitcnt lgkmcnt(2)
	v_mfma_f32_16x16x32_bf16 v[174:177], v[194:197], v[190:193], v[174:177]
	v_cvt_pk_bf16_f32 v186, v208, v202
	v_cvt_pk_bf16_f32 v187, v203, v204
	v_cvt_pk_bf16_f32 v188, v179, v181
	v_cvt_pk_bf16_f32 v189, v205, v198
	ds_read_b64_tr_b16 v[194:195], v35
	ds_read_b64_tr_b16 v[196:197], v35 offset:2048
	v_add_u32_e32 v35, v34, v162
	s_waitcnt lgkmcnt(2)
	v_mfma_f32_16x16x32_bf16 v[42:45], v[42:45], v[190:193], v[170:173]
	s_nop 2
	ds_read_b64_tr_b16 v[170:171], v35
	ds_read_b64_tr_b16 v[172:173], v35 offset:2048
	v_add_u32_e32 v35, v34, v163
	v_add_u32_e32 v34, v34, v164
	v_mfma_f32_16x16x32_bf16 v[166:169], v[30:33], v[190:193], v[166:169]
	ds_read_b64_tr_b16 v[190:191], v35
	ds_read_b64_tr_b16 v[192:193], v35 offset:2048
	v_add_u32_e32 v178, s11, v160
	v_add_u32_e32 v179, v178, v163
	s_waitcnt lgkmcnt(4)
	v_mfma_f32_16x16x32_bf16 v[182:185], v[194:197], v[186:189], v[182:185]
	ds_read_b64_tr_b16 v[194:195], v34
	ds_read_b64_tr_b16 v[196:197], v34 offset:2048
	s_waitcnt lgkmcnt(4)
	v_mfma_f32_16x16x32_bf16 v[38:41], v[170:173], v[186:189], v[38:41]
	v_exp_f32_e32 v172, v26
	v_exp_f32_e32 v170, v36
	v_exp_f32_e32 v171, v37
	v_mfma_f32_16x16x32_bf16 v[166:169], v[30:33], v[186:189], v[166:169]
	v_exp_f32_e32 v173, v27
	s_waitcnt lgkmcnt(2)
	v_mfma_f32_16x16x32_bf16 v[34:37], v[190:193], v[186:189], v[174:177]
	s_nop 2
	v_exp_f32_e32 v174, v28
	v_exp_f32_e32 v175, v29
	s_waitcnt lgkmcnt(0)
; __device__ __forceinline__ unsigned cvt_pk_bf16(float lo, float hi) { unsigned r; asm volatile("v_cvt_pk_bf16_f32 %0, %1, %2" : "=v"(r) : "v"(lo), "v"(hi)); return r; }
; #define LAS __attribute__((address_space(3)))
; __device__ __forceinline__ float bf_lo(unsigned u) { return __uint_as_float(u << 16); }
; __device__ __forceinline__ float bf_hi(unsigned u) { return __uint_as_float(u & 0xffff0000u); }
; __device__ __forceinline__ f32x4 mfma16(bf16x8 a, bf16x8 b, f32x4 c) { return __builtin_amdgcn_mfma_f32_16x16x32_bf16(a, b, c, 0, 0, 0); }
; #define LBAR() asm volatile("s_waitcnt lgkmcnt(0)\n\ts_barrier" ::: "memory")
; __device__ __forceinline__ void na_strip(const Params& P, LAS unsigned char* lds, int strip, int hsel, int tid, int lane, int wave) {
;     ...
;                 o[dt] = mfma16(va, pb, o[dt]); }
;             osum = mfma16(ones8, pb, osum);
;         }
;         const float inv = __builtin_amdgcn_rcpf(osum[0]);
; #pragma unroll
;         for (int dt = 0; dt < 4; ++dt) {
;             u32x2 w; w.x = cvt_pk_bf16(o[dt][0] * inv * bf_lo(gv[dt].x), o[dt][1] * inv * bf_hi(gv[dt].x)); w.y = cvt_pk_bf16(o[dt][2] * inv * bf_lo(gv[dt].y), o[dt][3] * inv * bf_hi(gv[dt].y));
;             *(u32x2*)(MIX + tq * DM + h * 64 + 16 * dt + 4 * g) = w; }
;         LBAR();
;         if (need0) { const unsigned sl = (unsigned)(nr0 % 9) * 8192u; *(LAS u32x4*)(lds + sl + kdst) = nk0; *(LAS u32x4*)(lds + sl + vdst) = nv0; }
;         if (need1) { const unsigned sl = (unsigned)(nr1 % 9) * 8192u; *(LAS u32x4*)(lds + sl + kdst) = nk1; *(LAS u32x4*)(lds + sl + vdst) = nv1; }
	v_mfma_f32_16x16x32_bf16 v[26:29], v[194:197], v[186:189], v[42:45]
	v_cvt_pk_bf16_f32 v42, v199, v200
	v_cvt_pk_bf16_f32 v43, v170, v171
	v_cvt_pk_bf16_f32 v44, v172, v173
	v_add_u32_e32 v172, v178, v161
	v_add_u32_e32 v176, v178, v162
	v_cvt_pk_bf16_f32 v45, v174, v175
	ds_read_b64_tr_b16 v[170:171], v172
	ds_read_b64_tr_b16 v[172:173], v172 offset:2048
	ds_read_b64_tr_b16 v[174:175], v176
	ds_read_b64_tr_b16 v[176:177], v176 offset:2048
	v_mfma_f32_16x16x32_bf16 v[30:33], v[30:33], v[42:45], v[166:169]
	s_waitcnt lgkmcnt(0)
	v_mfma_f32_16x16x32_bf16 v[38:41], v[174:177], v[42:45], v[38:41]
	v_add_u32_e32 v176, v178, v164
	s_nop 4
	v_rcp_f32_e32 v166, v30
	s_waitcnt vmcnt(3)
	v_lshlrev_b32_e32 v33, 16, v60
	v_mfma_f32_16x16x32_bf16 v[170:173], v[170:173], v[42:45], v[182:185]
	s_nop 2
	ds_read_b64_tr_b16 v[182:183], v179
	ds_read_b64_tr_b16 v[184:185], v179 offset:2048
	ds_read_b64_tr_b16 v[174:175], v176
	ds_read_b64_tr_b16 v[176:177], v176 offset:2048
	v_lshlrev_b64 v[30:31], 11, v[52:53]
	v_mul_f32_e32 v32, v170, v166
	s_waitcnt lgkmcnt(2)
	v_mfma_f32_16x16x32_bf16 v[34:37], v[182:185], v[42:45], v[34:37]
	v_mul_f32_e32 v32, v32, v33
	v_mul_f32_e32 v33, v171, v166
	v_lshl_add_u64 v[30:31], v[50:51], 0, v[30:31]
	v_mov_b32_e32 v243, 0
	v_bfe_u32 v242, v180, 4, 1
	v_mul_u32_u24_e32 v242, 24, v242
	v_lshl_add_u64 v[242:243], v[30:31], 0, v[242:243]
	s_waitcnt lgkmcnt(0)
	v_mfma_f32_16x16x32_bf16 v[26:29], v[174:177], v[42:45], v[26:29]
	v_and_b32_e32 v42, 0xffff0000, v60
	v_mul_f32_e32 v33, v33, v42
	v_cvt_pk_bf16_f32 v244, v32, v33
	v_mul_f32_e32 v33, v172, v166
	v_lshlrev_b32_e32 v42, 16, v61
	v_mul_f32_e32 v33, v33, v42
	v_mul_f32_e32 v42, v173, v166
	v_and_b32_e32 v43, 0xffff0000, v61
	v_mul_f32_e32 v42, v42, v43
	v_cvt_pk_bf16_f32 v245, v33, v42
	s_mov_b64 exec, 1
	global_store_dword v[242:243], v244, off
	s_mov_b64 exec, -1
	v_mul_f32_e32 v32, v38, v166
	s_waitcnt vmcnt(3)
	v_lshlrev_b32_e32 v33, 16, v58
	v_mul_f32_e32 v32, v32, v33
	v_mul_f32_e32 v33, v39, v166
	v_and_b32_e32 v38, 0xffff0000, v58
	v_mul_f32_e32 v33, v33, v38
	v_cvt_pk_bf16_f32 v246, v32, v33
	v_mul_f32_e32 v33, v40, v166
	v_lshlrev_b32_e32 v38, 16, v59
	v_mul_f32_e32 v33, v33, v38
	v_mul_f32_e32 v38, v41, v166
	v_and_b32_e32 v39, 0xffff0000, v59
	v_mul_f32_e32 v38, v38, v39
	v_cvt_pk_bf16_f32 v247, v33, v38
	s_nop 1
	v_permlane16_swap_b32_e32 v244, v246
	v_permlane16_swap_b32_e32 v245, v247
	global_store_dwordx4 v[242:243], v[244:247], off
	v_mul_f32_e32 v32, v34, v166
	s_waitcnt vmcnt(3)
	v_lshlrev_b32_e32 v33, 16, v56
	v_mul_f32_e32 v32, v32, v33
	v_mul_f32_e32 v33, v35, v166
	v_and_b32_e32 v34, 0xffff0000, v56
	v_mul_f32_e32 v33, v33, v34
	v_cvt_pk_bf16_f32 v244, v32, v33
	v_mul_f32_e32 v33, v36, v166
	v_lshlrev_b32_e32 v34, 16, v57
	v_mul_f32_e32 v33, v33, v34
	v_mul_f32_e32 v34, v37, v166
	v_and_b32_e32 v35, 0xffff0000, v57
	v_mul_f32_e32 v34, v34, v35
	v_cvt_pk_bf16_f32 v245, v33, v34
	s_mov_b64 exec, 1
	global_store_dword v[242:243], v244, off offset:64
	s_mov_b64 exec, -1
	v_mul_f32_e32 v26, v26, v166
	s_waitcnt vmcnt(3)
	v_lshlrev_b32_e32 v32, 16, v54
	v_mul_f32_e32 v26, v26, v32
	v_mul_f32_e32 v27, v27, v166
	v_and_b32_e32 v32, 0xffff0000, v54
	v_mul_f32_e32 v27, v27, v32
	v_cvt_pk_bf16_f32 v246, v26, v27
	v_mul_f32_e32 v27, v28, v166
	v_lshlrev_b32_e32 v28, 16, v55
	v_mul_f32_e32 v27, v27, v28
	v_mul_f32_e32 v28, v29, v166
	v_and_b32_e32 v29, 0xffff0000, v55
	v_mul_f32_e32 v28, v28, v29
	v_cvt_pk_bf16_f32 v247, v27, v28
	s_nop 1
	v_permlane16_swap_b32_e32 v244, v246
	v_permlane16_swap_b32_e32 v245, v247
	global_store_dwordx4 v[242:243], v[244:247], off offset:64
	s_waitcnt lgkmcnt(0)
	s_barrier
	s_cbranch_vccnz .LBB0_305
	s_mul_i32 s4, s12, 0xe38f
	s_lshr_b32 s4, s4, 19
	s_mul_i32 s4, s4, 9
	s_sub_i32 s4, s12, s4
	s_and_b32 s4, s4, 0xffff
	s_lshl_b32 s4, s4, 13
	s_add_i32 s4, s4, 0
	v_add_u32_e32 v26, s4, v67
	ds_write_b128 v26, v[2:5]
	v_add_u32_e32 v26, s4, v81
	ds_write_b128 v26, v[6:9]
